# st7: rw_mix 12 mix-weight vec4 loads issued before the row loop into spare VGPRs (copied after the tile barrier); rwkv_post Bs tile global loads issued ahead of the workgroup barrier
# speedup vs baseline: 1.0011x; 1.0011x over previous
; #define LAS __attribute__((address_space(3)))
; DI void rwkv_post_tile(int j, int item, LAS unsigned char* lds) {
;     ...
;     for (int nc = ncq * 2; nc < ncq * 2 + 2; ++nc) {
;         __syncthreads();
;         for (int i = 0; i < 6; ++i) { const int idx = tid + 512 * i; const int row = idx / 24, ch = idx - row * 24;
;             *(LAS u32x4*)(Bs + row * 200 + ch * 8) = *(const u32x4*)(G2 + (size_t)(nc * 128 + row) * 192 + ch * 8); }
;         __syncthreads();
;         f32x4 acc[8];
; #pragma unroll
;         for (int i = 0; i < 8; ++i) acc[i] = (f32x4){0.f, 0.f, 0.f, 0.f};
;         mm16<8, 6>(As + wave * 16 * 200, 200, Bs, 200, acc, fr, fq);
.LBB0_100:
	v_lshl_add_u64 v[2:3], s[12:13], 0, v[70:71]
	v_lshl_add_u64 v[6:7], s[12:13], 0, v[74:75]
	v_lshl_add_u64 v[10:11], s[12:13], 0, v[76:77]
	v_lshl_add_u64 v[14:15], s[12:13], 0, v[78:79]
	v_lshl_add_u64 v[18:19], s[12:13], 0, v[82:83]
	v_lshl_add_u64 v[22:23], s[12:13], 0, v[84:85]
	global_load_dwordx4 v[2:5], v[2:3], off
	s_nop 0
	global_load_dwordx4 v[6:9], v[6:7], off
	s_nop 0
	global_load_dwordx4 v[10:13], v[10:11], off
	s_nop 0
	global_load_dwordx4 v[14:17], v[14:15], off
	s_nop 0
	global_load_dwordx4 v[18:21], v[18:19], off
	s_nop 0
	global_load_dwordx4 v[22:25], v[22:23], off
	s_waitcnt lgkmcnt(0)
	s_barrier
	s_mov_b32 s2, 0x7000000
	v_lshl_add_u64 v[68:69], s[12:13], 0, v[72:73]
	v_lshl_add_u64 v[94:95], v[88:89], 0, s[14:15]
	v_lshl_add_u64 v[96:97], v[86:87], 0, s[14:15]
	v_mov_b32_e32 v116, v1
	v_mov_b32_e32 v118, v1
	v_mov_b32_e32 v164, 0x3a27c5ac
	s_mov_b32 s4, 0x3c800000
	s_add_u32 s14, s14, 0x200
	s_addc_u32 s15, s15, 0
	v_lshl_add_u64 v[70:71], v[70:71], 0, s[24:25]
	v_lshl_add_u64 v[72:73], v[72:73], 0, 8
	v_lshl_add_u64 v[74:75], v[74:75], 0, s[24:25]
	v_lshl_add_u64 v[76:77], v[76:77], 0, s[24:25]
	v_lshl_add_u64 v[78:79], v[78:79], 0, s[24:25]
	v_lshl_add_u64 v[82:83], v[82:83], 0, s[24:25]
	v_lshl_add_u64 v[84:85], v[84:85], 0, s[24:25]
	s_cmpk_lg_i32 s14, 0x400
	s_waitcnt vmcnt(5)
	ds_write_b128 v167, v[2:5]
	s_waitcnt vmcnt(4)
	ds_write_b128 v168, v[6:9]
	s_waitcnt vmcnt(3)
	ds_write_b128 v169, v[10:13]
	s_waitcnt vmcnt(2)
	ds_write_b128 v170, v[14:17]
	s_waitcnt vmcnt(1)
	ds_write_b128 v171, v[18:21]
	s_waitcnt vmcnt(0)
	ds_write_b128 v172, v[22:25]
	s_waitcnt lgkmcnt(0)
	s_barrier
	ds_read_b128 v[2:5], v173
	ds_read_b128 v[10:13], v139
	ds_read_b128 v[6:9], v139 offset:64
	ds_read_b128 v[22:25], v173 offset:64
	ds_read_b128 v[14:17], v173 offset:6400
	ds_read_b128 v[58:61], v173 offset:6464
	s_waitcnt lgkmcnt(1)
	v_mfma_f32_16x16x32_bf16 v[62:65], v[14:17], v[10:13], 0
	ds_read_b128 v[14:17], v173 offset:12800
	ds_read_b128 v[50:53], v173 offset:12864
	s_waitcnt lgkmcnt(1)
	v_mfma_f32_16x16x32_bf16 v[54:57], v[14:17], v[10:13], 0
	ds_read_b128 v[14:17], v173 offset:19200
	ds_read_b128 v[42:45], v173 offset:19264
	s_waitcnt lgkmcnt(1)
	v_mfma_f32_16x16x32_bf16 v[46:49], v[14:17], v[10:13], 0
	ds_read_b128 v[14:17], v173 offset:25600
	ds_read_b128 v[34:37], v173 offset:25664
	s_waitcnt lgkmcnt(1)
	v_mfma_f32_16x16x32_bf16 v[38:41], v[14:17], v[10:13], 0
	ds_read_b128 v[18:21], v173 offset:32000
	ds_read_b128 v[14:17], v173 offset:32064
	ds_read_b128 v[30:33], v173 offset:38400
	ds_read_b128 v[26:29], v173 offset:38464
	v_mfma_f32_16x16x32_bf16 v[42:45], v[42:45], v[6:9], v[46:49]
	s_nop 2
	ds_read_b128 v[46:49], v173 offset:128
	v_mfma_f32_16x16x32_bf16 v[2:5], v[2:5], v[10:13], 0
	s_waitcnt lgkmcnt(4)
	v_mfma_f32_16x16x32_bf16 v[18:21], v[18:21], v[10:13], 0
	s_waitcnt lgkmcnt(2)
	v_mfma_f32_16x16x32_bf16 v[30:33], v[30:33], v[10:13], 0
	v_mfma_f32_16x16x32_bf16 v[22:25], v[22:25], v[6:9], v[2:5]
	v_mfma_f32_16x16x32_bf16 v[34:37], v[34:37], v[6:9], v[38:41]
	v_mfma_f32_16x16x32_bf16 v[38:41], v[14:17], v[6:9], v[18:21]
	s_waitcnt lgkmcnt(1)
	v_mfma_f32_16x16x32_bf16 v[26:29], v[26:29], v[6:9], v[30:33]
	s_nop 0
	ds_read_b128 v[18:21], v139 offset:128
	ds_read_b128 v[14:17], v139 offset:192
	ds_read_b128 v[30:33], v173 offset:192
	v_mfma_f32_16x16x32_bf16 v[2:5], v[58:61], v[6:9], v[62:65]
	v_lshl_add_u64 v[58:59], s[12:13], 0, v[80:81]
	v_add_co_u32_e32 v92, vcc, s2, v58
	v_mfma_f32_16x16x32_bf16 v[50:53], v[50:53], v[6:9], v[54:57]
	s_nop 0
	v_addc_co_u32_e32 v93, vcc, 0, v59, vcc
	s_mov_b32 s2, 0xb400000
	s_waitcnt lgkmcnt(2)
	v_mfma_f32_16x16x32_bf16 v[22:25], v[46:49], v[18:21], v[22:25]
	ds_read_b128 v[46:49], v173 offset:6528
	ds_read_b128 v[54:57], v173 offset:6592
	v_add_co_u32_e32 v98, vcc, s2, v58
	s_waitcnt lgkmcnt(1)
	v_mfma_f32_16x16x32_bf16 v[2:5], v[46:49], v[18:21], v[2:5]
	ds_read_b128 v[46:49], v173 offset:12928
	ds_read_b128 v[60:63], v173 offset:12992
	v_addc_co_u32_e32 v99, vcc, 0, v59, vcc
	s_waitcnt lgkmcnt(1)
	v_mfma_f32_16x16x32_bf16 v[46:49], v[46:49], v[18:21], v[50:53]
	s_nop 2
	ds_read_b128 v[50:53], v173 offset:19328
	ds_read_b128 v[64:67], v173 offset:19392
	s_mov_b32 s2, 0x1e600000
	v_add_co_u32_e32 v100, vcc, s2, v68
	s_waitcnt lgkmcnt(1)
	v_mfma_f32_16x16x32_bf16 v[42:45], v[50:53], v[18:21], v[42:45]
	ds_read_b128 v[50:53], v173 offset:25728
	ds_read_b128 v[104:107], v173 offset:25792
	v_addc_co_u32_e32 v101, vcc, 0, v69, vcc
	s_waitcnt lgkmcnt(1)
	v_mfma_f32_16x16x32_bf16 v[34:37], v[50:53], v[18:21], v[34:37]
	ds_read_b128 v[50:53], v173 offset:32128
	ds_read_b128 v[108:111], v173 offset:32192
	s_mov_b32 s2, 0x1e820000
	v_add_co_u32_e32 v102, vcc, s2, v68
	s_waitcnt lgkmcnt(1)
	v_mfma_f32_16x16x32_bf16 v[38:41], v[50:53], v[18:21], v[38:41]
	ds_read_b128 v[50:53], v173 offset:38528
	ds_read_b128 v[112:115], v173 offset:38592
	v_addc_co_u32_e32 v103, vcc, 0, v69, vcc
	s_brev_b32 s2, 24
	v_add_co_u32_e32 v136, vcc, s2, v58
	s_mov_b32 s2, 0xf800000
	s_nop 0
	v_addc_co_u32_e32 v137, vcc, 0, v59, vcc
	v_mfma_f32_16x16x32_bf16 v[30:33], v[30:33], v[14:17], v[22:25]
	v_add_co_u32_e32 v90, vcc, s2, v58
	global_load_dwordx2 v[144:145], v[92:93], off
	global_load_dwordx2 v[146:147], v[98:99], off
	ds_read_b128 v[22:25], v139 offset:256
	s_waitcnt lgkmcnt(2)
; DI void rwkv_post_tile(int j, int item, LAS unsigned char* lds) {
;     ...
;             const int H = nc * 2 + hh; float y[4][4]; float sum = 0.f;
; #pragma unroll
;             for (int q = 0; q < 4; ++q) { const int c = nc * 128 + (hh * 4 + q) * 16 + fq * 4;
;                 const u32x2 a = *(const u32x2*)(Y0 + m * D + c), bq = *(const u32x2*)(Y1 + m * D + c);
;                 y[q][0] = bflo(a.x) + bflo(bq.x); y[q][1] = bfhi(a.x) + bfhi(bq.x); y[q][2] = bflo(a.y) + bflo(bq.y); y[q][3] = bfhi(a.y) + bfhi(bq.y);
;                 sum += y[q][0] + y[q][1] + y[q][2] + y[q][3]; }
;             sum += __shfl_xor(sum, 16); sum += __shfl_xor(sum, 32);
;             const float mean = sum * (1.f / 64.f); float vs = 0.f;
; #pragma unroll
;             for (int q = 0; q < 4; ++q)
; #pragma unroll
;                 for (int e = 0; e < 4; ++e) { y[q][e] -= mean; vs += y[q][e] * y[q][e]; }
;             vs += __shfl_xor(vs, 16); vs += __shfl_xor(vs, 32);
;             const float rstd = rsqrtf(vs * (1.f / 64.f) + 64e-5f);
	v_mfma_f32_16x16x32_bf16 v[26:29], v[50:53], v[18:21], v[26:29]
	v_addc_co_u32_e32 v91, vcc, 0, v59, vcc
	v_lshl_add_u64 v[80:81], v[80:81], 0, s[16:17]
	v_mfma_f32_16x16x32_bf16 v[50:53], v[54:57], v[14:17], v[2:5]
	v_mfma_f32_16x16x32_bf16 v[46:49], v[60:63], v[14:17], v[46:49]
	ds_read_b128 v[54:57], v173 offset:256
	ds_read_b128 v[58:61], v173 offset:6656
	global_load_dwordx2 v[148:149], v[98:99], off offset:32
	global_load_dwordx2 v[150:151], v[92:93], off offset:32
	v_mfma_f32_16x16x32_bf16 v[42:45], v[64:67], v[14:17], v[42:45]
	ds_read_b128 v[62:65], v173 offset:13056
	ds_read_b128 v[66:69], v173 offset:19456
	s_waitcnt vmcnt(1)
	v_and_b32_e32 v199, 0xffff0000, v148
	v_mfma_f32_16x16x32_bf16 v[34:37], v[104:107], v[14:17], v[34:37]
	v_mfma_f32_16x16x32_bf16 v[38:41], v[108:111], v[14:17], v[38:41]
	ds_read_b128 v[2:5], v139 offset:320
	ds_read_b128 v[108:111], v173 offset:320
	global_load_dwordx2 v[152:153], v[92:93], off offset:64
	global_load_dwordx2 v[154:155], v[98:99], off offset:64
	s_waitcnt lgkmcnt(7)
	v_mfma_f32_16x16x32_bf16 v[104:107], v[112:115], v[14:17], v[26:29]
	ds_read_b128 v[112:115], v173 offset:6720
	s_waitcnt vmcnt(1)
	v_lshlrev_b32_e32 v202, 16, v153
	s_waitcnt lgkmcnt(6)
	v_mfma_f32_16x16x32_bf16 v[54:57], v[54:57], v[22:25], v[30:33]
	ds_read_b128 v[26:29], v173 offset:25856
	s_nop 1
	ds_read_b128 v[30:33], v173 offset:32256
	ds_read_b128 v[120:123], v173 offset:13120
	ds_read_b128 v[124:127], v173 offset:38656
	ds_read_b128 v[128:131], v173 offset:19520
	global_load_dwordx2 v[156:157], v[92:93], off offset:96
	global_load_dwordx2 v[158:159], v[98:99], off offset:96
	ds_read_b128 v[132:135], v173 offset:25920
	global_load_dword v0, v[100:101], off
	global_load_dword v117, v[102:103], off
	global_load_dwordx2 v[160:161], v[136:137], off
	s_waitcnt lgkmcnt(11)
	v_mfma_f32_16x16x32_bf16 v[50:53], v[58:61], v[22:25], v[50:53]
	global_load_dwordx4 v[58:61], v[94:95], off
	s_waitcnt vmcnt(6)
	v_lshlrev_b32_e32 v200, 16, v154
	v_and_b32_e32 v201, 0xffff0000, v154
	s_waitcnt lgkmcnt(10)
	v_mfma_f32_16x16x32_bf16 v[46:49], v[62:65], v[22:25], v[46:49]
	global_load_dwordx4 v[62:65], v[96:97], off
	v_and_b32_e32 v154, 0xffff0000, v153
	v_lshlrev_b32_e32 v203, 16, v155
	s_waitcnt lgkmcnt(5)
	v_mfma_f32_16x16x32_bf16 v[140:143], v[26:29], v[22:25], v[34:37]
	ds_read_b128 v[26:29], v173 offset:38720
	v_and_b32_e32 v155, 0xffff0000, v155
	s_waitcnt vmcnt(6)
	v_lshlrev_b32_e32 v153, 16, v157
	ds_read_b128 v[34:37], v173 offset:32320
	s_waitcnt lgkmcnt(6)
	v_mfma_f32_16x16x32_bf16 v[38:41], v[30:33], v[22:25], v[38:41]
	s_waitcnt vmcnt(5)
	v_and_b32_e32 v204, 0xffff0000, v159
	v_lshlrev_b32_e32 v205, 16, v159
	v_and_b32_e32 v206, 0xffff0000, v156
	s_waitcnt lgkmcnt(4)
	v_mfma_f32_16x16x32_bf16 v[30:33], v[124:127], v[22:25], v[104:107]
	global_load_dwordx2 v[124:125], v[136:137], off offset:32
	global_load_dwordx2 v[126:127], v[136:137], off offset:64
	global_load_dwordx2 v[162:163], v[136:137], off offset:96
	global_load_dwordx2 v[174:175], v[92:93], off offset:128
	global_load_dwordx2 v[176:177], v[98:99], off offset:128
	global_load_dwordx2 v[178:179], v[98:99], off offset:160
	global_load_dwordx2 v[180:181], v[92:93], off offset:160
	global_load_dwordx2 v[188:189], v[92:93], off offset:192
	global_load_dwordx2 v[190:191], v[92:93], off offset:224
	global_load_dwordx2 v[192:193], v[98:99], off offset:192
	global_load_dwordx2 v[194:195], v[98:99], off offset:224
	global_load_dwordx2 v[106:107], v[136:137], off offset:128
	v_mfma_f32_16x16x32_bf16 v[42:45], v[66:69], v[22:25], v[42:45]
	global_load_dwordx2 v[98:99], v[136:137], off offset:192
	global_load_dwordx2 v[104:105], v[136:137], off offset:160
	global_load_dwordx2 v[92:93], v[136:137], off offset:224
	v_and_b32_e32 v137, 0xffff0000, v145
	v_and_b32_e32 v136, 0xffff0000, v144
	v_mfma_f32_16x16x32_bf16 v[66:69], v[108:111], v[2:5], v[54:57]
	v_lshlrev_b32_e32 v207, 16, v156
	v_and_b32_e32 v156, 0xffff0000, v158
	s_waitcnt vmcnt(18)
	v_add_f32_e32 v0, v0, v117
	v_mfma_f32_16x16x32_bf16 v[54:57], v[112:115], v[2:5], v[50:53]
	s_waitcnt vmcnt(13)
	v_lshlrev_b32_e32 v113, 16, v127
	v_mfma_f32_16x16x32_bf16 v[50:53], v[120:123], v[2:5], v[46:49]
	v_mov_b32_e32 v110, v66
	v_mov_b32_e32 v111, v68
	v_mov_b32_e32 v68, v67
	s_waitcnt lgkmcnt(3)
	v_mfma_f32_16x16x32_bf16 v[46:49], v[128:131], v[2:5], v[42:45]
	v_mov_b32_e32 v108, v54
	v_mov_b32_e32 v109, v56
	v_mov_b32_e32 v56, v55
	s_waitcnt lgkmcnt(2)
	v_mfma_f32_16x16x32_bf16 v[42:45], v[132:135], v[2:5], v[140:143]
	v_mov_b32_e32 v66, v50
	v_mov_b32_e32 v67, v52
	v_mov_b32_e32 v52, v51
	v_mov_b32_e32 v54, v46
	v_mov_b32_e32 v55, v48
	v_mov_b32_e32 v48, v47
	s_nop 1
	v_mov_b32_e32 v50, v42
	v_mov_b32_e32 v51, v44
	v_mov_b32_e32 v44, v43
	v_lshlrev_b32_e32 v43, 16, v145
	v_lshlrev_b32_e32 v42, 16, v144
	v_lshlrev_b32_e32 v47, 16, v147
	v_lshlrev_b32_e32 v46, 16, v146
	v_and_b32_e32 v141, 0xffff0000, v147
	v_and_b32_e32 v140, 0xffff0000, v146
	v_lshlrev_b32_e32 v142, 16, v148
	v_lshlrev_b32_e32 v144, 16, v150
	v_and_b32_e32 v147, 0xffff0000, v150
	v_lshlrev_b32_e32 v145, 16, v151
	v_and_b32_e32 v148, 0xffff0000, v151
	v_lshlrev_b32_e32 v150, 16, v152
	v_and_b32_e32 v151, 0xffff0000, v152
	v_and_b32_e32 v152, 0xffff0000, v157
	v_lshlrev_b32_e32 v157, 16, v158
	v_lshlrev_b32_e32 v129, 16, v161
	v_lshlrev_b32_e32 v128, 16, v160
	v_and_b32_e32 v131, 0xffff0000, v161
	v_and_b32_e32 v130, 0xffff0000, v160
	v_lshlrev_b32_e32 v121, 16, v125
	v_lshlrev_b32_e32 v120, 16, v124
	v_and_b32_e32 v123, 0xffff0000, v125
	v_and_b32_e32 v122, 0xffff0000, v124
	v_lshlrev_b32_e32 v112, 16, v126
	v_and_b32_e32 v115, 0xffff0000, v127
	v_and_b32_e32 v114, 0xffff0000, v126
	s_waitcnt vmcnt(11)
; DI void rwkv_post_tile(int j, int item, LAS unsigned char* lds) {
;     ...
;             const int H = nc * 2 + hh; float y[4][4]; float sum = 0.f;
; #pragma unroll
;             for (int q = 0; q < 4; ++q) { const int c = nc * 128 + (hh * 4 + q) * 16 + fq * 4;
;                 const u32x2 a = *(const u32x2*)(Y0 + m * D + c), bq = *(const u32x2*)(Y1 + m * D + c);
;                 y[q][0] = bflo(a.x) + bflo(bq.x); y[q][1] = bfhi(a.x) + bfhi(bq.x); y[q][2] = bflo(a.y) + bflo(bq.y); y[q][3] = bfhi(a.y) + bfhi(bq.y);
;                 sum += y[q][0] + y[q][1] + y[q][2] + y[q][3]; }
;             sum += __shfl_xor(sum, 16); sum += __shfl_xor(sum, 32);
;             const float mean = sum * (1.f / 64.f); float vs = 0.f;
; #pragma unroll
;             for (int q = 0; q < 4; ++q)
; #pragma unroll
;                 for (int e = 0; e < 4; ++e) { y[q][e] -= mean; vs += y[q][e] * y[q][e]; }
;             vs += __shfl_xor(vs, 16); vs += __shfl_xor(vs, 32);
	v_lshlrev_b32_e32 v125, 16, v175
	v_lshlrev_b32_e32 v124, 16, v174
	s_waitcnt vmcnt(10)
	v_lshlrev_b32_e32 v127, 16, v177
	v_lshlrev_b32_e32 v126, 16, v176
	v_and_b32_e32 v159, 0xffff0000, v175
	v_and_b32_e32 v158, 0xffff0000, v174
	v_and_b32_e32 v161, 0xffff0000, v177
	v_and_b32_e32 v160, 0xffff0000, v176
	v_lshlrev_b32_e32 v143, 16, v149
	v_and_b32_e32 v149, 0xffff0000, v149
	v_mov_b32_e32 v132, v58
	v_mov_b32_e32 v133, v60
	v_mov_b32_e32 v134, v62
	v_mov_b32_e32 v135, v64
	v_mov_b32_e32 v60, v59
	v_mov_b32_e32 v64, v63
	v_lshlrev_b32_e32 v59, 16, v163
	v_lshlrev_b32_e32 v58, 16, v162
	v_and_b32_e32 v63, 0xffff0000, v163
	v_and_b32_e32 v62, 0xffff0000, v162
	s_waitcnt vmcnt(9)
	v_lshlrev_b32_e32 v162, 16, v178
	s_waitcnt vmcnt(8)
	v_lshlrev_b32_e32 v174, 16, v180
	v_and_b32_e32 v177, 0xffff0000, v180
	v_and_b32_e32 v209, 0xffff0000, v178
	v_lshlrev_b32_e32 v163, 16, v179
	v_lshlrev_b32_e32 v175, 16, v181
	v_and_b32_e32 v178, 0xffff0000, v181
	s_waitcnt vmcnt(7)
	v_lshlrev_b32_e32 v180, 16, v188
	v_and_b32_e32 v181, 0xffff0000, v188
	s_waitcnt vmcnt(5)
	v_lshlrev_b32_e32 v210, 16, v192
	v_and_b32_e32 v211, 0xffff0000, v192
	v_lshlrev_b32_e32 v213, 16, v193
	v_and_b32_e32 v193, 0xffff0000, v193
	v_and_b32_e32 v192, 0xffff0000, v189
	v_pk_add_f32 v[42:43], v[42:43], v[46:47]
	v_pk_add_f32 v[46:47], v[136:137], v[140:141]
	v_pk_add_f32 v[124:125], v[124:125], v[126:127]
	v_pk_add_f32 v[126:127], v[158:159], v[160:161]
	v_and_b32_e32 v179, 0xffff0000, v179
	v_lshlrev_b32_e32 v212, 16, v189
	v_and_b32_e32 v188, 0xffff0000, v191
	v_lshlrev_b32_e32 v189, 16, v191
	v_and_b32_e32 v216, 0xffff0000, v190
	v_lshlrev_b32_e32 v217, 16, v190
	s_waitcnt vmcnt(4)
	v_and_b32_e32 v190, 0xffff0000, v194
	v_lshlrev_b32_e32 v191, 16, v194
	v_pk_add_f32 v[136:137], v[144:145], v[142:143]
	v_pk_add_f32 v[140:141], v[148:149], v[148:149] op_sel:[1,0] op_sel_hi:[0,1]
	v_pk_add_f32 v[142:143], v[150:151], v[200:201]
	v_mov_b32_e32 v144, v203
	v_pk_add_f32 v[148:149], v[154:155], v[154:155] op_sel:[1,0] op_sel_hi:[0,1]
	v_pk_add_f32 v[150:151], v[152:153], v[204:205]
	v_pk_add_f32 v[152:153], v[206:207], v[156:157]
	v_pk_add_f32 v[160:161], v[174:175], v[162:163]
	v_pk_add_f32 v[156:157], v[180:181], v[210:211]
	v_pk_add_f32 v[162:163], v[192:193], v[192:193] op_sel:[1,0] op_sel_hi:[0,1]
	v_mov_b32_e32 v146, v42
	v_mov_b32_e32 v198, v46
	v_mov_b32_e32 v176, v124
	v_mov_b32_e32 v208, v126
	v_and_b32_e32 v214, 0xffff0000, v195
	v_lshlrev_b32_e32 v215, 16, v195
	v_pk_add_f32 v[154:155], v[178:179], v[178:179] op_sel:[1,0] op_sel_hi:[0,1]
	v_pk_add_f32 v[178:179], v[216:217], v[190:191]
	v_pk_mov_b32 v[180:181], v[42:43], v[136:137] op_sel:[1,0]
	v_pk_add_f32 v[144:145], v[144:145], v[202:203]
	v_pk_add_f32 v[190:191], v[142:143], v[142:143] op_sel:[0,1] op_sel_hi:[1,0]
	v_mov_b32_e32 v192, v148
	v_mov_b32_e32 v194, v142
	v_pk_mov_b32 v[142:143], v[142:143], v[148:149] op_sel:[1,0]
	v_pk_mov_b32 v[148:149], v[124:125], v[160:161] op_sel:[1,0]
	v_pk_add_f32 v[202:203], v[156:157], v[156:157] op_sel:[0,1] op_sel_hi:[1,0]
	v_mov_b32_e32 v204, v162
	v_mov_b32_e32 v206, v156
	v_pk_mov_b32 v[162:163], v[156:157], v[162:163] op_sel:[1,0]
	v_pk_add_f32 v[146:147], v[146:147], v[198:199]
	v_pk_add_f32 v[156:157], v[176:177], v[208:209]
	v_mov_b32_e32 v158, v213
	v_pk_add_f32 v[174:175], v[188:189], v[214:215]
	v_mov_b32_e32 v188, v47
	v_mov_b32_e32 v189, v137
	v_mov_b32_e32 v117, v140
	v_mov_b32_e32 v200, v127
	v_mov_b32_e32 v201, v161
	v_pk_add_f32 v[176:177], v[180:181], v[146:147]
	v_pk_mov_b32 v[140:141], v[146:147], v[140:141] op_sel:[1,0]
	v_pk_add_f32 v[146:147], v[148:149], v[156:157]
	v_mov_b32_e32 v119, v154
	v_pk_add_f32 v[158:159], v[158:159], v[212:213]
	v_pk_mov_b32 v[180:181], v[156:157], v[154:155] op_sel:[1,0]
	v_pk_add_f32 v[154:155], v[188:189], v[176:177]
	v_pk_add_f32 v[146:147], v[200:201], v[146:147]
	v_mov_b32_e32 v145, v153
	v_mov_b32_e32 v191, v152
	v_mov_b32_e32 v159, v179
	v_mov_b32_e32 v203, v178
	v_pk_add_f32 v[116:117], v[154:155], v[116:117]
	v_pk_add_f32 v[118:119], v[146:147], v[118:119]
	v_mov_b32_e32 v193, v151
	v_mov_b32_e32 v205, v175
	v_mov_b32_e32 v195, v144
	v_pk_add_f32 v[144:145], v[144:145], v[190:191]
	v_pk_add_f32 v[148:149], v[158:159], v[202:203]
	v_pk_add_f32 v[116:117], v[116:117], v[116:117] op_sel:[0,1] op_sel_hi:[1,0]
	v_pk_add_f32 v[118:119], v[118:119], v[118:119] op_sel:[0,1] op_sel_hi:[1,0]
	v_pk_add_f32 v[144:145], v[192:193], v[144:145]
	v_pk_add_f32 v[148:149], v[204:205], v[148:149]
	v_mov_b32_e32 v117, v150
	v_mov_b32_e32 v119, v174
	v_pk_add_f32 v[116:117], v[116:117], v[144:145]
	v_pk_add_f32 v[118:119], v[118:119], v[148:149]
	v_add_f32_e32 v116, v116, v117
	v_add_f32_e32 v117, v118, v119
	ds_bpermute_b32 v118, v165, v116
	ds_bpermute_b32 v119, v165, v117
	v_mov_b32_e32 v207, v158
	s_waitcnt lgkmcnt(2)
	v_mfma_f32_16x16x32_bf16 v[34:37], v[34:37], v[2:5], v[38:41]
	s_waitcnt lgkmcnt(1)
	v_add_f32_e32 v116, v116, v118
	s_waitcnt lgkmcnt(0)
	v_add_f32_e32 v117, v117, v119
	ds_bpermute_b32 v118, v166, v116
	ds_bpermute_b32 v119, v166, v117
	s_waitcnt vmcnt(1)
	v_and_b32_e32 v41, 0xffff0000, v105
	v_and_b32_e32 v40, 0xffff0000, v104
	v_mov_b32_e32 v38, v34
	s_waitcnt lgkmcnt(1)
	v_add_f32_e32 v116, v116, v118
	s_waitcnt lgkmcnt(0)
; DI unsigned pk2(float lo, float hi) { return f2bf(lo) | (f2bf(hi) << 16); }
; DI void rwkv_post_tile(int j, int item, LAS unsigned char* lds) {
;     ...
;             sum += __shfl_xor(sum, 16); sum += __shfl_xor(sum, 32);
;             const float mean = sum * (1.f / 64.f); float vs = 0.f;
; #pragma unroll
;             for (int q = 0; q < 4; ++q)
; #pragma unroll
;                 for (int e = 0; e < 4; ++e) { y[q][e] -= mean; vs += y[q][e] * y[q][e]; }
;             vs += __shfl_xor(vs, 16); vs += __shfl_xor(vs, 32);
;             const float rstd = rsqrtf(vs * (1.f / 64.f) + 64e-5f);
;             const float sb = SB0[m * 16 + H] + SB1[m * 16 + H];
; #pragma unroll
;             for (int q = 0; q < 4; ++q) { const int c = nc * 128 + (hh * 4 + q) * 16 + fq * 4;
;                 const u32x2 vu = *(const u32x2*)(Vb + m * D + c); const float vf[4] = {bflo(vu.x), bfhi(vu.x), bflo(vu.y), bfhi(vu.y)};
;                 float o[4];
; #pragma unroll
;                 for (int e = 0; e < 4; ++e) o[e] = (y[q][e] * rstd * lng[c + e] + lnb[c + e] + sb * vf[e]) * acc[hh * 4 + q][e];
;                 u32x2 w; w.x = pk2(o[0], o[1]); w.y = pk2(o[2], o[3]);
;                 *(u32x2*)(Yo + m * D + c) = w; }
	v_add_f32_e32 v117, v117, v119
	v_mul_f32_e32 v116, 0x3c800000, v116
	v_mul_f32_e32 v118, 0x3c800000, v117
	v_pk_add_f32 v[176:177], v[150:151], v[116:117] op_sel_hi:[1,0] neg_lo:[0,1] neg_hi:[0,1]
	v_pk_add_f32 v[150:151], v[46:47], v[116:117] op_sel_hi:[1,0] neg_lo:[0,1] neg_hi:[0,1]
	v_pk_add_f32 v[144:145], v[126:127], v[118:119] op_sel_hi:[1,0] neg_lo:[0,1] neg_hi:[0,1]
	v_pk_add_f32 v[146:147], v[152:153], v[116:117] op_sel_hi:[1,0] neg_lo:[0,1] neg_hi:[0,1]
	v_pk_add_f32 v[148:149], v[42:43], v[116:117] op_sel_hi:[1,0] neg_lo:[0,1] neg_hi:[0,1]
	v_pk_add_f32 v[152:153], v[136:137], v[116:117] op_sel_hi:[1,0] neg_lo:[0,1] neg_hi:[0,1]
	v_pk_add_f32 v[42:43], v[178:179], v[118:119] op_sel_hi:[1,0] neg_lo:[0,1] neg_hi:[0,1]
	v_pk_add_f32 v[46:47], v[174:175], v[118:119] op_sel_hi:[1,0] neg_lo:[0,1] neg_hi:[0,1]
	v_pk_add_f32 v[136:137], v[124:125], v[118:119] op_sel_hi:[1,0] neg_lo:[0,1] neg_hi:[0,1]
	v_mov_b32_e32 v192, v144
	v_mov_b32_e32 v193, v150
	v_pk_add_f32 v[154:155], v[140:141], v[116:117] op_sel_hi:[1,0] neg_lo:[0,1] neg_hi:[0,1]
	v_pk_add_f32 v[158:159], v[142:143], v[116:117] op_sel_hi:[1,0] neg_lo:[0,1] neg_hi:[0,1]
	v_pk_add_f32 v[124:125], v[160:161], v[118:119] op_sel_hi:[1,0] neg_lo:[0,1] neg_hi:[0,1]
	v_pk_mul_f32 v[140:141], v[146:147], v[146:147]
	v_pk_mul_f32 v[142:143], v[176:177], v[176:177]
	v_mov_b32_e32 v160, v147
	v_mov_b32_e32 v161, v177
	v_mov_b32_e32 v147, v176
	v_pk_mul_f32 v[176:177], v[42:43], v[42:43]
	v_pk_mul_f32 v[178:179], v[46:47], v[46:47]
	v_mov_b32_e32 v190, v136
	v_mov_b32_e32 v191, v148
	v_pk_mul_f32 v[192:193], v[192:193], v[192:193]
	v_pk_add_f32 v[156:157], v[194:195], v[116:117] op_sel_hi:[1,0] neg_lo:[0,1] neg_hi:[0,1]
	v_mov_b32_e32 v194, v137
	v_mov_b32_e32 v195, v149
	v_mov_b32_e32 v208, v177
	v_mov_b32_e32 v209, v141
	v_mov_b32_e32 v177, v140
	v_mov_b32_e32 v140, v179
	v_mov_b32_e32 v141, v143
	v_mov_b32_e32 v179, v142
	v_pk_fma_f32 v[142:143], v[190:191], v[190:191], v[192:193]
	v_mov_b32_e32 v198, v145
	v_mov_b32_e32 v199, v151
	v_pk_fma_f32 v[142:143], v[194:195], v[194:195], v[142:143]
	v_pk_add_f32 v[126:127], v[180:181], v[118:119] op_sel_hi:[1,0] neg_lo:[0,1] neg_hi:[0,1]
	v_mov_b32_e32 v200, v124
	v_mov_b32_e32 v201, v152
	v_pk_fma_f32 v[142:143], v[198:199], v[198:199], v[142:143]
	v_pk_add_f32 v[116:117], v[206:207], v[118:119] op_sel_hi:[1,0] neg_lo:[0,1] neg_hi:[0,1]
	v_pk_add_f32 v[118:119], v[162:163], v[118:119] op_sel_hi:[1,0] neg_lo:[0,1] neg_hi:[0,1]
	v_mov_b32_e32 v202, v126
	v_mov_b32_e32 v203, v154
	v_pk_fma_f32 v[142:143], v[200:201], v[200:201], v[142:143]
	v_mov_b32_e32 v162, v158
	v_mov_b32_e32 v163, v156
	v_mov_b32_e32 v180, v118
	v_mov_b32_e32 v181, v116
	v_mov_b32_e32 v204, v125
	v_mov_b32_e32 v205, v153
	v_pk_fma_f32 v[142:143], v[202:203], v[202:203], v[142:143]
	v_mov_b32_e32 v206, v127
	v_mov_b32_e32 v207, v155
	v_pk_mul_f32 v[162:163], v[162:163], v[162:163]
	v_pk_mul_f32 v[180:181], v[180:181], v[180:181]
	v_pk_fma_f32 v[142:143], v[204:205], v[204:205], v[142:143]
	v_mov_b32_e32 v174, v159
	v_mov_b32_e32 v175, v157
	v_mov_b32_e32 v188, v119
	v_mov_b32_e32 v189, v117
	v_mov_b32_e32 v190, v181
	v_mov_b32_e32 v191, v163
	v_pk_fma_f32 v[142:143], v[206:207], v[206:207], v[142:143]
	v_pk_mul_f32 v[174:175], v[174:175], v[174:175]
	v_pk_mul_f32 v[188:189], v[188:189], v[188:189]
	v_mov_b32_e32 v181, v162
	v_pk_add_f32 v[142:143], v[190:191], v[142:143]
	v_mov_b32_e32 v162, v189
	v_mov_b32_e32 v163, v175
	v_pk_add_f32 v[142:143], v[180:181], v[142:143]
	v_mov_b32_e32 v189, v174
	v_pk_add_f32 v[142:143], v[162:163], v[142:143]
	v_mov_b32_e32 v39, v36
	v_pk_add_f32 v[142:143], v[188:189], v[142:143]
	v_mov_b32_e32 v36, v35
	v_pk_add_f32 v[142:143], v[208:209], v[142:143]
	v_lshlrev_b32_e32 v35, 16, v105
	v_pk_add_f32 v[142:143], v[176:177], v[142:143]
	v_lshlrev_b32_e32 v34, 16, v104
	v_pk_add_f32 v[140:141], v[140:141], v[142:143]
	v_mfma_f32_16x16x32_bf16 v[26:29], v[26:29], v[2:5], v[30:33]
	v_add_f32_e64 v140, v178, v140
	v_add_f32_e64 v141, v179, v141
	ds_bpermute_b32 v143, v165, v141
	ds_bpermute_b32 v142, v165, v140
	v_and_b32_e32 v33, 0xffff0000, v99
	v_and_b32_e32 v32, 0xffff0000, v98
	s_nop 1
	v_mov_b32_e32 v30, v26
	v_mov_b32_e32 v31, v28
	s_waitcnt lgkmcnt(0)
	v_pk_add_f32 v[140:141], v[140:141], v[142:143]
	ds_bpermute_b32 v143, v166, v141
	ds_bpermute_b32 v142, v166, v140
	v_mov_b32_e32 v28, v27
	v_lshlrev_b32_e32 v27, 16, v99
	v_lshlrev_b32_e32 v26, 16, v98
	s_waitcnt lgkmcnt(0)
	v_pk_add_f32 v[162:163], v[140:141], v[142:143]
	s_nop 0
	v_pk_fma_f32 v[140:141], v[162:163], s[4:5], v[164:165] op_sel_hi:[1,0,0]
	s_nop 0
	v_mul_f32_e32 v142, 0x4b800000, v141
	v_cmp_gt_f32_e64 s[4:5], s3, v141
	v_mul_f32_e32 v162, 0x4b800000, v140
	v_cmp_gt_f32_e32 vcc, s3, v140
	v_cndmask_b32_e64 v141, v141, v142, s[4:5]
	v_rsq_f32_e32 v141, v141
	s_nop 0
	v_mul_f32_e32 v142, 0x45800000, v141
	v_cndmask_b32_e64 v142, v141, v142, s[4:5]
	v_pk_mul_f32 v[150:151], v[150:151], v[142:143] op_sel_hi:[1,0]
	v_pk_mul_f32 v[148:149], v[148:149], v[142:143] op_sel_hi:[1,0]
	v_pk_fma_f32 v[60:61], v[60:61], v[150:151], v[64:65]
	v_pk_fma_f32 v[132:133], v[132:133], v[148:149], v[134:135]
	v_pk_fma_f32 v[60:61], v[0:1], v[130:131], v[60:61] op_sel_hi:[0,1,1]
	v_pk_fma_f32 v[64:65], v[0:1], v[128:129], v[132:133] op_sel_hi:[0,1,1]
	v_pk_mul_f32 v[60:61], v[68:69], v[60:61]
	v_pk_mul_f32 v[64:65], v[110:111], v[64:65]
	v_and_b32_sdwa v110, v61, v186 dst_sel:DWORD dst_unused:UNUSED_PAD src0_sel:WORD_1 src1_sel:DWORD
	v_and_b32_sdwa v111, v60, v186 dst_sel:DWORD dst_unused:UNUSED_PAD src0_sel:WORD_1 src1_sel:DWORD
	v_and_b32_sdwa v68, v65, v186 dst_sel:DWORD dst_unused:UNUSED_PAD src0_sel:WORD_1 src1_sel:DWORD
	v_and_b32_sdwa v69, v64, v186 dst_sel:DWORD dst_unused:UNUSED_PAD src0_sel:WORD_1 src1_sel:DWORD
	v_add3_u32 v61, v61, v110, s31
	v_add3_u32 v60, v60, v111, s31
	v_add3_u32 v64, v64, v69, s31
	v_add3_u32 v65, v65, v68, s31
	v_and_b32_e32 v61, 0xffff0000, v61
	v_and_b32_e32 v60, 0xffff0000, v60
	v_or_b32_sdwa v61, v61, v65 dst_sel:DWORD dst_unused:UNUSED_PAD src0_sel:DWORD src1_sel:WORD_1
	v_or_b32_sdwa v60, v60, v64 dst_sel:DWORD dst_unused:UNUSED_PAD src0_sel:DWORD src1_sel:WORD_1
	global_load_dwordx4 v[244:247], v[94:95], off offset:64
	global_load_dwordx4 v[248:251], v[96:97], off offset:64
	global_store_dwordx2 v[90:91], v[60:61], off
	v_pk_mul_f32 v[152:153], v[152:153], v[142:143] op_sel_hi:[1,0]
	v_pk_mul_f32 v[154:155], v[154:155], v[142:143] op_sel_hi:[1,0]
	v_pk_mul_f32 v[156:157], v[156:157], v[142:143] op_sel_hi:[1,0]
	v_pk_mul_f32 v[158:159], v[158:159], v[142:143] op_sel_hi:[1,0]
	v_pk_mul_f32 v[160:161], v[160:161], v[142:143] op_sel_hi:[1,0]
	v_pk_mul_f32 v[142:143], v[146:147], v[142:143] op_sel_hi:[1,0]
	s_waitcnt vmcnt(2)
; DI unsigned pk2(float lo, float hi) { return f2bf(lo) | (f2bf(hi) << 16); }
; DI void rwkv_post_tile(int j, int item, LAS unsigned char* lds) {
;     ...
;             const float sb = SB0[m * 16 + H] + SB1[m * 16 + H];
; #pragma unroll
;             for (int q = 0; q < 4; ++q) { const int c = nc * 128 + (hh * 4 + q) * 16 + fq * 4;
;                 const u32x2 vu = *(const u32x2*)(Vb + m * D + c); const float vf[4] = {bflo(vu.x), bfhi(vu.x), bflo(vu.y), bfhi(vu.y)};
;                 float o[4];
; #pragma unroll
;                 for (int e = 0; e < 4; ++e) o[e] = (y[q][e] * rstd * lng[c + e] + lnb[c + e] + sb * vf[e]) * acc[hh * 4 + q][e];
;                 u32x2 w; w.x = pk2(o[0], o[1]); w.y = pk2(o[2], o[3]);
;                 *(u32x2*)(Yo + m * D + c) = w; }
	v_mov_b64_e32 v[128:129], v[244:245]
	v_mov_b64_e32 v[130:131], v[246:247]
	v_mov_b32_e32 v60, v128
	v_mov_b32_e32 v61, v130
	s_waitcnt vmcnt(1)
	v_mov_b64_e32 v[132:133], v[248:249]
	v_mov_b64_e32 v[134:135], v[250:251]
	v_mov_b32_e32 v64, v132
	v_mov_b32_e32 v65, v134
	v_mov_b32_e32 v130, v129
	v_mov_b32_e32 v134, v133
	v_pk_fma_f32 v[60:61], v[60:61], v[152:153], v[64:65]
	v_pk_fma_f32 v[64:65], v[130:131], v[154:155], v[134:135]
	v_pk_fma_f32 v[60:61], v[0:1], v[120:121], v[60:61] op_sel_hi:[0,1,1]
	v_pk_fma_f32 v[64:65], v[0:1], v[122:123], v[64:65] op_sel_hi:[0,1,1]
	v_pk_mul_f32 v[56:57], v[56:57], v[64:65]
	v_pk_mul_f32 v[60:61], v[108:109], v[60:61]
	v_and_b32_sdwa v68, v57, v186 dst_sel:DWORD dst_unused:UNUSED_PAD src0_sel:WORD_1 src1_sel:DWORD
	v_and_b32_sdwa v69, v56, v186 dst_sel:DWORD dst_unused:UNUSED_PAD src0_sel:WORD_1 src1_sel:DWORD
	v_and_b32_sdwa v64, v61, v186 dst_sel:DWORD dst_unused:UNUSED_PAD src0_sel:WORD_1 src1_sel:DWORD
	v_and_b32_sdwa v65, v60, v186 dst_sel:DWORD dst_unused:UNUSED_PAD src0_sel:WORD_1 src1_sel:DWORD
	v_add3_u32 v57, v57, v68, s31
	v_add3_u32 v56, v56, v69, s31
	v_add3_u32 v60, v60, v65, s31
	v_add3_u32 v61, v61, v64, s31
	v_and_b32_e32 v57, 0xffff0000, v57
	v_and_b32_e32 v56, 0xffff0000, v56
	v_or_b32_sdwa v57, v57, v61 dst_sel:DWORD dst_unused:UNUSED_PAD src0_sel:DWORD src1_sel:WORD_1
	v_or_b32_sdwa v56, v56, v60 dst_sel:DWORD dst_unused:UNUSED_PAD src0_sel:DWORD src1_sel:WORD_1
	global_load_dwordx4 v[244:247], v[94:95], off offset:128
	global_load_dwordx4 v[248:251], v[96:97], off offset:128
	global_store_dwordx2 v[90:91], v[56:57], off offset:32
	s_waitcnt vmcnt(2)
	v_mov_b64_e32 v[108:109], v[244:245]
	v_mov_b64_e32 v[110:111], v[246:247]
	v_mov_b32_e32 v56, v108
	v_mov_b32_e32 v57, v110
	s_waitcnt vmcnt(1)
	v_mov_b64_e32 v[120:121], v[248:249]
	v_mov_b64_e32 v[122:123], v[250:251]
	v_mov_b32_e32 v60, v120
	v_mov_b32_e32 v61, v122
	v_mov_b32_e32 v110, v109
	v_mov_b32_e32 v122, v121
	v_pk_fma_f32 v[56:57], v[56:57], v[156:157], v[60:61]
	v_pk_fma_f32 v[60:61], v[110:111], v[158:159], v[122:123]
	v_pk_fma_f32 v[56:57], v[0:1], v[112:113], v[56:57] op_sel_hi:[0,1,1]
	v_pk_fma_f32 v[60:61], v[0:1], v[114:115], v[60:61] op_sel_hi:[0,1,1]
	v_pk_mul_f32 v[52:53], v[52:53], v[60:61]
	v_pk_mul_f32 v[56:57], v[66:67], v[56:57]
	v_and_b32_sdwa v64, v53, v186 dst_sel:DWORD dst_unused:UNUSED_PAD src0_sel:WORD_1 src1_sel:DWORD
	v_and_b32_sdwa v65, v52, v186 dst_sel:DWORD dst_unused:UNUSED_PAD src0_sel:WORD_1 src1_sel:DWORD
	v_and_b32_sdwa v60, v57, v186 dst_sel:DWORD dst_unused:UNUSED_PAD src0_sel:WORD_1 src1_sel:DWORD
	v_and_b32_sdwa v61, v56, v186 dst_sel:DWORD dst_unused:UNUSED_PAD src0_sel:WORD_1 src1_sel:DWORD
	v_add3_u32 v53, v53, v64, s31
	v_add3_u32 v52, v52, v65, s31
	v_add3_u32 v56, v56, v61, s31
	v_add3_u32 v57, v57, v60, s31
	v_and_b32_e32 v53, 0xffff0000, v53
	v_and_b32_e32 v52, 0xffff0000, v52
	v_or_b32_sdwa v53, v53, v57 dst_sel:DWORD dst_unused:UNUSED_PAD src0_sel:DWORD src1_sel:WORD_1
	v_or_b32_sdwa v52, v52, v56 dst_sel:DWORD dst_unused:UNUSED_PAD src0_sel:DWORD src1_sel:WORD_1
	global_load_dwordx4 v[244:247], v[94:95], off offset:192
	global_load_dwordx4 v[248:251], v[96:97], off offset:192
	global_store_dwordx2 v[90:91], v[52:53], off offset:64
	s_waitcnt vmcnt(2)
	v_mov_b64_e32 v[64:65], v[244:245]
	v_mov_b64_e32 v[66:67], v[246:247]
	v_mov_b32_e32 v52, v64
	v_mov_b32_e32 v53, v66
	s_waitcnt vmcnt(1)
	v_mov_b64_e32 v[108:109], v[248:249]
	v_mov_b64_e32 v[110:111], v[250:251]
	v_mov_b32_e32 v56, v108
	v_mov_b32_e32 v57, v110
	v_mov_b32_e32 v66, v65
	v_mov_b32_e32 v110, v109
	v_pk_fma_f32 v[52:53], v[52:53], v[160:161], v[56:57]
	v_pk_fma_f32 v[56:57], v[142:143], v[66:67], v[110:111]
	v_pk_fma_f32 v[52:53], v[0:1], v[58:59], v[52:53] op_sel_hi:[0,1,1]
	v_pk_fma_f32 v[56:57], v[0:1], v[62:63], v[56:57] op_sel_hi:[0,1,1]
	v_pk_mul_f32 v[48:49], v[48:49], v[56:57]
	v_pk_mul_f32 v[52:53], v[54:55], v[52:53]
	v_and_b32_sdwa v55, v49, v186 dst_sel:DWORD dst_unused:UNUSED_PAD src0_sel:WORD_1 src1_sel:DWORD
	v_and_b32_sdwa v56, v48, v186 dst_sel:DWORD dst_unused:UNUSED_PAD src0_sel:WORD_1 src1_sel:DWORD
	v_and_b32_sdwa v0, v53, v186 dst_sel:DWORD dst_unused:UNUSED_PAD src0_sel:WORD_1 src1_sel:DWORD
	v_and_b32_sdwa v54, v52, v186 dst_sel:DWORD dst_unused:UNUSED_PAD src0_sel:WORD_1 src1_sel:DWORD
	v_add3_u32 v49, v49, v55, s31
	v_add3_u32 v48, v48, v56, s31
	v_add3_u32 v52, v52, v54, s31
	v_add3_u32 v0, v53, v0, s31
	v_and_b32_e32 v49, 0xffff0000, v49
	v_and_b32_e32 v48, 0xffff0000, v48
	v_or_b32_sdwa v49, v49, v0 dst_sel:DWORD dst_unused:UNUSED_PAD src0_sel:DWORD src1_sel:WORD_1
	v_or_b32_sdwa v48, v48, v52 dst_sel:DWORD dst_unused:UNUSED_PAD src0_sel:DWORD src1_sel:WORD_1
	global_load_dwordx4 v[244:247], v[94:95], off offset:256
	global_load_dwordx4 v[248:251], v[96:97], off offset:256
	global_load_dword v236, v[100:101], off offset:4
	global_load_dword v237, v[102:103], off offset:4
	global_store_dwordx2 v[90:91], v[48:49], off offset:96
	v_cndmask_b32_e32 v48, v140, v162, vcc
	v_rsq_f32_e32 v48, v48
	v_and_b32_e32 v67, 0xffff0000, v107
	v_and_b32_e32 v66, 0xffff0000, v106
	v_lshlrev_b32_e32 v65, 16, v107
	v_mul_f32_e32 v60, 0x45800000, v48
	v_cndmask_b32_e32 v48, v48, v60, vcc
	v_lshlrev_b32_e32 v64, 16, v106
	s_waitcnt vmcnt(4)
	v_mov_b64_e32 v[52:53], v[244:245]
	v_mov_b64_e32 v[54:55], v[246:247]
	v_mov_b32_e32 v69, v54
	s_waitcnt vmcnt(3)
	v_mov_b64_e32 v[56:57], v[248:249]
	v_mov_b64_e32 v[58:59], v[250:251]
	v_mov_b32_e32 v101, v58
	v_mov_b32_e32 v54, v53
	s_waitcnt vmcnt(1)
; DI unsigned pk2(float lo, float hi) { return f2bf(lo) | (f2bf(hi) << 16); }
; DI void rwkv_post_tile(int j, int item, LAS unsigned char* lds) {
;     ...
;             const float sb = SB0[m * 16 + H] + SB1[m * 16 + H];
; #pragma unroll
;             for (int q = 0; q < 4; ++q) { const int c = nc * 128 + (hh * 4 + q) * 16 + fq * 4;
;                 const u32x2 vu = *(const u32x2*)(Vb + m * D + c); const float vf[4] = {bflo(vu.x), bfhi(vu.x), bflo(vu.y), bfhi(vu.y)};
;                 float o[4];
; #pragma unroll
;                 for (int e = 0; e < 4; ++e) o[e] = (y[q][e] * rstd * lng[c + e] + lnb[c + e] + sb * vf[e]) * acc[hh * 4 + q][e];
;                 u32x2 w; w.x = pk2(o[0], o[1]); w.y = pk2(o[2], o[3]);
;                 *(u32x2*)(Yo + m * D + c) = w; }
	v_mov_b32_e32 v0, v236
	v_mov_b32_e32 v49, v237
	v_pk_mul_f32 v[62:63], v[144:145], v[48:49] op_sel_hi:[1,0]
	v_mov_b32_e32 v58, v57
	v_pk_mul_f32 v[60:61], v[136:137], v[48:49] op_sel_hi:[1,0]
	v_add_f32_e32 v0, v0, v49
	v_mov_b32_e32 v68, v52
	v_mov_b32_e32 v100, v56
	v_pk_fma_f32 v[54:55], v[54:55], v[62:63], v[58:59]
	v_pk_fma_f32 v[52:53], v[68:69], v[60:61], v[100:101]
	v_pk_fma_f32 v[54:55], v[0:1], v[66:67], v[54:55] op_sel_hi:[0,1,1]
	v_pk_fma_f32 v[52:53], v[0:1], v[64:65], v[52:53] op_sel_hi:[0,1,1]
	v_pk_mul_f32 v[44:45], v[44:45], v[54:55]
	v_pk_mul_f32 v[50:51], v[50:51], v[52:53]
	v_and_b32_sdwa v53, v45, v186 dst_sel:DWORD dst_unused:UNUSED_PAD src0_sel:WORD_1 src1_sel:DWORD
	v_and_b32_sdwa v54, v44, v186 dst_sel:DWORD dst_unused:UNUSED_PAD src0_sel:WORD_1 src1_sel:DWORD
	v_and_b32_sdwa v49, v51, v186 dst_sel:DWORD dst_unused:UNUSED_PAD src0_sel:WORD_1 src1_sel:DWORD
	v_and_b32_sdwa v52, v50, v186 dst_sel:DWORD dst_unused:UNUSED_PAD src0_sel:WORD_1 src1_sel:DWORD
	v_add3_u32 v45, v45, v53, s31
	v_add3_u32 v44, v44, v54, s31
	v_add3_u32 v50, v50, v52, s31
	v_add3_u32 v49, v51, v49, s31
	v_and_b32_e32 v45, 0xffff0000, v45
	v_and_b32_e32 v44, 0xffff0000, v44
	v_or_b32_sdwa v45, v45, v49 dst_sel:DWORD dst_unused:UNUSED_PAD src0_sel:DWORD src1_sel:WORD_1
	v_or_b32_sdwa v44, v44, v50 dst_sel:DWORD dst_unused:UNUSED_PAD src0_sel:DWORD src1_sel:WORD_1
	global_load_dwordx4 v[244:247], v[94:95], off offset:320
	global_load_dwordx4 v[248:251], v[96:97], off offset:320
	global_store_dwordx2 v[90:91], v[44:45], off offset:128
	v_pk_mul_f32 v[58:59], v[126:127], v[48:49] op_sel_hi:[1,0]
	v_pk_mul_f32 v[44:45], v[124:125], v[48:49] op_sel_hi:[1,0]
	s_waitcnt vmcnt(2)
	v_mov_b64_e32 v[50:51], v[244:245]
	v_mov_b64_e32 v[52:53], v[246:247]
	v_mov_b32_e32 v61, v52
	s_waitcnt vmcnt(1)
	v_mov_b64_e32 v[54:55], v[248:249]
	v_mov_b64_e32 v[56:57], v[250:251]
	v_mov_b32_e32 v63, v56
	v_mov_b32_e32 v52, v51
	v_mov_b32_e32 v56, v55
	v_mov_b32_e32 v60, v50
	v_mov_b32_e32 v62, v54
	v_pk_fma_f32 v[50:51], v[52:53], v[58:59], v[56:57]
	v_pk_fma_f32 v[44:45], v[60:61], v[44:45], v[62:63]
	v_pk_fma_f32 v[40:41], v[0:1], v[40:41], v[50:51] op_sel_hi:[0,1,1]
	v_pk_fma_f32 v[34:35], v[0:1], v[34:35], v[44:45] op_sel_hi:[0,1,1]
	v_pk_mul_f32 v[36:37], v[36:37], v[40:41]
	v_pk_mul_f32 v[34:35], v[38:39], v[34:35]
	v_and_b32_sdwa v40, v37, v186 dst_sel:DWORD dst_unused:UNUSED_PAD src0_sel:WORD_1 src1_sel:DWORD
	v_and_b32_sdwa v41, v36, v186 dst_sel:DWORD dst_unused:UNUSED_PAD src0_sel:WORD_1 src1_sel:DWORD
	v_and_b32_sdwa v38, v35, v186 dst_sel:DWORD dst_unused:UNUSED_PAD src0_sel:WORD_1 src1_sel:DWORD
	v_and_b32_sdwa v39, v34, v186 dst_sel:DWORD dst_unused:UNUSED_PAD src0_sel:WORD_1 src1_sel:DWORD
	v_add3_u32 v37, v37, v40, s31
	v_add3_u32 v36, v36, v41, s31
	v_add3_u32 v34, v34, v39, s31
	v_add3_u32 v35, v35, v38, s31
	v_and_b32_e32 v37, 0xffff0000, v37
	v_and_b32_e32 v36, 0xffff0000, v36
	v_or_b32_sdwa v35, v37, v35 dst_sel:DWORD dst_unused:UNUSED_PAD src0_sel:DWORD src1_sel:WORD_1
	v_or_b32_sdwa v34, v36, v34 dst_sel:DWORD dst_unused:UNUSED_PAD src0_sel:DWORD src1_sel:WORD_1
	global_load_dwordx4 v[244:247], v[94:95], off offset:384
	global_load_dwordx4 v[248:251], v[96:97], off offset:384
	global_store_dwordx2 v[90:91], v[34:35], off offset:160
	v_pk_mul_f32 v[50:51], v[118:119], v[48:49] op_sel_hi:[1,0]
	v_pk_mul_f32 v[44:45], v[116:117], v[48:49] op_sel_hi:[1,0]
	s_waitcnt vmcnt(2)
	v_mov_b64_e32 v[34:35], v[244:245]
	v_mov_b64_e32 v[36:37], v[246:247]
	v_mov_b32_e32 v53, v36
	s_waitcnt vmcnt(1)
; DI unsigned pk2(float lo, float hi) { return f2bf(lo) | (f2bf(hi) << 16); }
; DI void rwkv_post_tile(int j, int item, LAS unsigned char* lds) {
;     ...
;         mm16<8, 6>(As + wave * 16 * 200, 200, Bs, 200, acc, fr, fq);
;     ...
;             for (int q = 0; q < 4; ++q) { const int c = nc * 128 + (hh * 4 + q) * 16 + fq * 4;
;                 const u32x2 vu = *(const u32x2*)(Vb + m * D + c); const float vf[4] = {bflo(vu.x), bfhi(vu.x), bflo(vu.y), bfhi(vu.y)};
;                 float o[4];
; #pragma unroll
;                 for (int e = 0; e < 4; ++e) o[e] = (y[q][e] * rstd * lng[c + e] + lnb[c + e] + sb * vf[e]) * acc[hh * 4 + q][e];
;                 u32x2 w; w.x = pk2(o[0], o[1]); w.y = pk2(o[2], o[3]);
;                 *(u32x2*)(Yo + m * D + c) = w; }
;         }
;     }
	v_mov_b64_e32 v[38:39], v[248:249]
	v_mov_b64_e32 v[40:41], v[250:251]
	v_mov_b32_e32 v55, v40
	v_mov_b32_e32 v36, v35
	v_mov_b32_e32 v40, v39
	v_mov_b32_e32 v52, v34
	v_mov_b32_e32 v54, v38
	v_pk_fma_f32 v[36:37], v[36:37], v[50:51], v[40:41]
	v_pk_fma_f32 v[34:35], v[52:53], v[44:45], v[54:55]
	v_pk_fma_f32 v[32:33], v[0:1], v[32:33], v[36:37] op_sel_hi:[0,1,1]
	v_pk_fma_f32 v[26:27], v[0:1], v[26:27], v[34:35] op_sel_hi:[0,1,1]
	v_pk_mul_f32 v[28:29], v[28:29], v[32:33]
	v_pk_mul_f32 v[26:27], v[30:31], v[26:27]
	v_and_b32_sdwa v32, v29, v186 dst_sel:DWORD dst_unused:UNUSED_PAD src0_sel:WORD_1 src1_sel:DWORD
	v_and_b32_sdwa v33, v28, v186 dst_sel:DWORD dst_unused:UNUSED_PAD src0_sel:WORD_1 src1_sel:DWORD
	v_and_b32_sdwa v30, v27, v186 dst_sel:DWORD dst_unused:UNUSED_PAD src0_sel:WORD_1 src1_sel:DWORD
	v_and_b32_sdwa v31, v26, v186 dst_sel:DWORD dst_unused:UNUSED_PAD src0_sel:WORD_1 src1_sel:DWORD
	v_add3_u32 v29, v29, v32, s31
	v_add3_u32 v28, v28, v33, s31
	v_add3_u32 v26, v26, v31, s31
	v_add3_u32 v27, v27, v30, s31
	v_and_b32_e32 v29, 0xffff0000, v29
	v_and_b32_e32 v28, 0xffff0000, v28
	v_or_b32_sdwa v27, v29, v27 dst_sel:DWORD dst_unused:UNUSED_PAD src0_sel:DWORD src1_sel:WORD_1
	v_or_b32_sdwa v26, v28, v26 dst_sel:DWORD dst_unused:UNUSED_PAD src0_sel:DWORD src1_sel:WORD_1
	global_load_dwordx4 v[244:247], v[94:95], off offset:448
	global_load_dwordx4 v[248:251], v[96:97], off offset:448
	global_store_dwordx2 v[90:91], v[26:27], off offset:192
	ds_read_b128 v[34:37], v173 offset:44800
	ds_read_b128 v[38:41], v173 offset:44864
	s_waitcnt lgkmcnt(1)
	v_mfma_f32_16x16x32_bf16 v[10:13], v[34:37], v[10:13], 0
	ds_read_b128 v[34:37], v173 offset:44928
	s_waitcnt lgkmcnt(1)
	v_mfma_f32_16x16x32_bf16 v[6:9], v[38:41], v[6:9], v[10:13]
	s_nop 4
	ds_read_b128 v[10:13], v173 offset:44992
	s_waitcnt lgkmcnt(1)
	v_mfma_f32_16x16x32_bf16 v[6:9], v[34:37], v[18:21], v[6:9]
	ds_read_b128 v[18:21], v173 offset:45056
	s_waitcnt lgkmcnt(1)
	v_mfma_f32_16x16x32_bf16 v[10:13], v[10:13], v[14:17], v[6:9]
	s_nop 4
	ds_read_b128 v[6:9], v173 offset:45120
	s_waitcnt vmcnt(2)
	v_mov_b64_e32 v[26:27], v[244:245]
	v_mov_b64_e32 v[28:29], v[246:247]
	v_mov_b32_e32 v14, v26
	s_waitcnt lgkmcnt(1)
	v_mfma_f32_16x16x32_bf16 v[10:13], v[18:21], v[22:25], v[10:13]
	v_mov_b32_e32 v15, v28
	s_waitcnt vmcnt(1)
	v_mov_b64_e32 v[30:31], v[248:249]
	v_mov_b64_e32 v[32:33], v[250:251]
	v_mov_b32_e32 v16, v30
	v_mov_b32_e32 v17, v32
	s_waitcnt lgkmcnt(0)
	v_mfma_f32_16x16x32_bf16 v[2:5], v[6:9], v[2:5], v[10:13]
	v_mov_b32_e32 v28, v27
	v_mov_b32_e32 v32, v31
	v_and_b32_e32 v9, 0xffff0000, v93
	v_mov_b32_e32 v10, v43
	v_mov_b32_e32 v11, v47
	v_mov_b32_e32 v43, v46
	v_pk_mul_f32 v[10:11], v[10:11], v[48:49] op_sel_hi:[1,0]
	v_pk_mul_f32 v[12:13], v[42:43], v[48:49] op_sel_hi:[1,0]
	v_mov_b32_e32 v6, v2
	v_mov_b32_e32 v7, v4
	v_mov_b32_e32 v4, v3
	v_lshlrev_b32_e32 v3, 16, v93
	v_lshlrev_b32_e32 v2, 16, v92
	v_and_b32_e32 v8, 0xffff0000, v92
	v_pk_fma_f32 v[10:11], v[14:15], v[10:11], v[16:17]
	v_pk_fma_f32 v[12:13], v[12:13], v[28:29], v[32:33]
	v_pk_fma_f32 v[2:3], v[0:1], v[2:3], v[10:11] op_sel_hi:[0,1,1]
	v_pk_fma_f32 v[8:9], v[0:1], v[8:9], v[12:13] op_sel_hi:[0,1,1]
	v_pk_mul_f32 v[2:3], v[6:7], v[2:3]
	v_pk_mul_f32 v[4:5], v[4:5], v[8:9]
	v_and_b32_sdwa v0, v3, v186 dst_sel:DWORD dst_unused:UNUSED_PAD src0_sel:WORD_1 src1_sel:DWORD
	v_and_b32_sdwa v7, v5, v186 dst_sel:DWORD dst_unused:UNUSED_PAD src0_sel:WORD_1 src1_sel:DWORD
	v_and_b32_sdwa v8, v4, v186 dst_sel:DWORD dst_unused:UNUSED_PAD src0_sel:WORD_1 src1_sel:DWORD
	v_and_b32_sdwa v6, v2, v186 dst_sel:DWORD dst_unused:UNUSED_PAD src0_sel:WORD_1 src1_sel:DWORD
	v_add3_u32 v0, v3, v0, s31
	v_add3_u32 v3, v5, v7, s31
	v_add3_u32 v4, v4, v8, s31
	v_add3_u32 v2, v2, v6, s31
	v_and_b32_e32 v3, 0xffff0000, v3
	v_and_b32_e32 v4, 0xffff0000, v4
	v_or_b32_sdwa v3, v3, v0 dst_sel:DWORD dst_unused:UNUSED_PAD src0_sel:DWORD src1_sel:WORD_1
	v_or_b32_sdwa v2, v4, v2 dst_sel:DWORD dst_unused:UNUSED_PAD src0_sel:DWORD src1_sel:WORD_1
	global_store_dwordx2 v[90:91], v[2:3], off offset:224
	s_cbranch_scc1 .LBB0_100
	s_barrier
	s_branch .LBB0_95

; #define BIDX() sgpr_opaque((int)__builtin_amdgcn_workgroup_id_x())
; #define GDIM() sgpr_opaque((int)__ockl_get_num_groups(0))
; DI void phase_rw_mix(int layer, int j, int q, LAS unsigned char* lds) {
;     ...
;     for (int it = BIDX(); it < QROWS / 17; it += GDIM()) {
;         const int lr0 = it * 17, m0 = q * QROWS + lr0; const int b = m0 / T, t0 = m0 - b * T;
;         __syncthreads();
;         for (int rr = wave; rr < 19; rr += 8) {
.LBB0_452:
	s_mul_i32 s21, s20, 17
	s_add_i32 s23, s21, s44
	s_mul_hi_i32 s2, s23, 0x78787879
	s_lshr_b32 s3, s2, 31
	s_ashr_i32 s24, s2, 11
	s_add_i32 s24, s24, s3
	s_mul_i32 s25, s24, 0x1100
	s_sub_i32 s22, s23, s25
	s_waitcnt vmcnt(0)
	s_barrier
	global_load_dwordx4 v[198:201], v[54:55], off
	global_load_dwordx4 v[202:205], v[56:57], off
	global_load_dwordx4 v[206:209], v[58:59], off
	global_load_dwordx4 v[210:213], v[60:61], off
	global_load_dwordx4 v[214:217], v[62:63], off
	global_load_dwordx4 v[218:221], v[64:65], off
	global_load_dwordx4 v[222:225], v[66:67], off
	global_load_dwordx4 v[226:229], v[68:69], off
	global_load_dwordx4 v[230:233], v[70:71], off
	global_load_dwordx4 v[236:239], v[72:73], off
	global_load_dwordx4 v[240:243], v[74:75], off
	global_load_dwordx4 v[244:247], v[76:77], off
	s_and_saveexec_b64 s[14:15], s[4:5]
	s_cbranch_execz .LBB0_463
	s_add_i32 s2, s22, -1
	s_mov_b64 s[16:17], 0
	s_add_i32 s25, s25, s2
	v_mov_b32_e32 v21, v87
	v_mov_b32_e32 v24, v86
	v_mov_b32_e32 v25, v84
	s_branch .LBB0_455

; DI void phase_rw_mix(int layer, int j, int q, LAS unsigned char* lds) {
;     ...
;         __syncthreads();
;         const int c4 = tid & 255, rh = tid >> 8;
;         f32x4 mu0[6], mu1[6];
; #pragma unroll
;         for (int i = 0; i < 6; ++i) { mu0[i] = *(const f32x4*)(mu + (size_t)(i * 2) * D + 4 * c4); mu1[i] = *(const f32x4*)(mu + (size_t)(i * 2 + 1) * D + 4 * c4); }
.LBB0_463:
	s_or_b64 exec, exec, s[14:15]
	s_waitcnt lgkmcnt(0)
	s_barrier
	s_mov_b32 s2, 0
	s_mov_b64 s[14:15], 0
	v_mov_b32_e32 v79, v85
	s_waitcnt vmcnt(0)
	v_mov_b64_e32 v[2:3], v[198:199]
	v_mov_b64_e32 v[4:5], v[200:201]
	v_mov_b64_e32 v[6:7], v[202:203]
	v_mov_b64_e32 v[8:9], v[204:205]
	v_mov_b64_e32 v[10:11], v[206:207]
	v_mov_b64_e32 v[12:13], v[208:209]
	v_mov_b64_e32 v[14:15], v[210:211]
	v_mov_b64_e32 v[16:17], v[212:213]
	v_mov_b64_e32 v[18:19], v[214:215]
	v_mov_b64_e32 v[20:21], v[216:217]
	v_mov_b64_e32 v[22:23], v[218:219]
	v_mov_b64_e32 v[24:25], v[220:221]
	v_mov_b64_e32 v[26:27], v[222:223]
	v_mov_b64_e32 v[28:29], v[224:225]
	v_mov_b64_e32 v[30:31], v[226:227]
	v_mov_b64_e32 v[32:33], v[228:229]
	v_mov_b64_e32 v[34:35], v[230:231]
	v_mov_b64_e32 v[36:37], v[232:233]
	v_mov_b64_e32 v[38:39], v[236:237]
	v_mov_b64_e32 v[40:41], v[238:239]
	v_mov_b64_e32 v[42:43], v[240:241]
	v_mov_b64_e32 v[44:45], v[242:243]
	v_mov_b64_e32 v[46:47], v[244:245]
	v_mov_b64_e32 v[48:49], v[246:247]
	s_branch .LBB0_465
